# stick-breaking attention: no wave priority raise around the MFMA bursts
# baseline (speedup 1.0000x reference)
.LBB0_41:
	s_add_i32 s0, s42, -1
	v_cmp_le_i32_e32 vcc, s2, v198
	s_and_b32 s45, s0, 1
	s_cbranch_vccnz .LBB0_44
	v_cmp_gt_f32_e32 vcc, s58, v172
	s_cmp_eq_u64 vcc, exec
	s_cbranch_scc1 .LBB0_44
	s_mul_i32 s0, s45, 0x8c00
	s_add_i32 s0, s0, 0
	v_add_u32_e32 v0, s0, v189
	v_add_u32_e32 v173, v0, v188
	ds_read_b128 v[66:69], v173
	ds_read_b128 v[174:177], v173 offset:32
	ds_read_b128 v[82:85], v173 offset:8704
	ds_read_b128 v[200:203], v173 offset:8736
	ds_read_b128 v[204:207], v173 offset:64
	ds_read_b128 v[208:211], v173 offset:96
	ds_read_b128 v[212:215], v173 offset:8768
	ds_read_b128 v[216:219], v173 offset:8800
	s_waitcnt lgkmcnt(7)
	v_mfma_f32_32x32x16_bf16 v[66:81], v[66:69], v[98:101], 0
	s_waitcnt lgkmcnt(5)
	v_mfma_f32_32x32x16_bf16 v[82:97], v[82:85], v[98:101], 0
	v_mfma_f32_32x32x16_bf16 v[66:81], v[174:177], v[102:105], v[66:81]
	s_waitcnt lgkmcnt(4)
	v_mfma_f32_32x32x16_bf16 v[82:97], v[200:203], v[102:105], v[82:97]
	s_waitcnt lgkmcnt(3)
	v_mfma_f32_32x32x16_bf16 v[66:81], v[204:207], v[106:109], v[66:81]
	s_waitcnt lgkmcnt(1)
	v_mfma_f32_32x32x16_bf16 v[82:97], v[212:215], v[106:109], v[82:97]
	v_mfma_f32_32x32x16_bf16 v[66:81], v[208:211], v[110:113], v[66:81]
	s_waitcnt lgkmcnt(0)
	v_mfma_f32_32x32x16_bf16 v[82:97], v[216:219], v[110:113], v[82:97]
	ds_read_b128 v[174:177], v173 offset:128
	ds_read_b128 v[200:203], v173 offset:160
	ds_read_b128 v[204:207], v173 offset:8832
	ds_read_b128 v[208:211], v173 offset:8864
	ds_read_b128 v[212:215], v173 offset:192
	ds_read_b128 v[216:219], v173 offset:224
	ds_read_b128 v[220:223], v173 offset:8896
	ds_read_b128 v[224:227], v173 offset:8928
	s_waitcnt lgkmcnt(7)
	v_mfma_f32_32x32x16_bf16 v[66:81], v[174:177], v[114:117], v[66:81]
	s_waitcnt lgkmcnt(5)
	v_mfma_f32_32x32x16_bf16 v[82:97], v[204:207], v[114:117], v[82:97]
	v_mfma_f32_32x32x16_bf16 v[66:81], v[200:203], v[118:121], v[66:81]
	s_waitcnt lgkmcnt(4)
	v_mfma_f32_32x32x16_bf16 v[82:97], v[208:211], v[118:121], v[82:97]
	s_waitcnt lgkmcnt(3)
	v_mfma_f32_32x32x16_bf16 v[66:81], v[212:215], v[122:125], v[66:81]
	s_waitcnt lgkmcnt(1)
	v_mfma_f32_32x32x16_bf16 v[82:97], v[220:223], v[122:125], v[82:97]
	v_mfma_f32_32x32x16_bf16 v[66:81], v[216:219], v[126:129], v[66:81]
	s_waitcnt lgkmcnt(0)
	v_mfma_f32_32x32x16_bf16 v[82:97], v[224:227], v[126:129], v[82:97]
	s_nop 10
	v_mov_b32_e32 v236, 1.0
	v_cmp_gt_i32_e32 vcc, 28, v159
	s_cmp_eq_u64 vcc, 0
	s_cbranch_scc1 .Lstk_nm1
	v_cmp_lt_i32_e64 s[0:1], 0, v159
	v_cmp_lt_i32_e64 s[8:9], 1, v159
	v_cmp_lt_i32_e64 s[10:11], 2, v159
	v_cmp_lt_i32_e64 s[12:13], 3, v159
	v_cndmask_b32_e64 v82, v231, v82, s[0:1]
	v_cndmask_b32_e64 v83, v231, v83, s[8:9]
	v_cndmask_b32_e64 v84, v231, v84, s[10:11]
	v_cndmask_b32_e64 v85, v231, v85, s[12:13]
	v_cmp_lt_i32_e64 s[0:1], 8, v159
	v_cmp_lt_i32_e64 s[8:9], 9, v159
	v_cmp_lt_i32_e64 s[10:11], 10, v159
	v_cmp_lt_i32_e64 s[12:13], 11, v159
	v_cndmask_b32_e64 v86, v231, v86, s[0:1]
	v_cndmask_b32_e64 v87, v231, v87, s[8:9]
	v_cndmask_b32_e64 v88, v231, v88, s[10:11]
	v_cndmask_b32_e64 v89, v231, v89, s[12:13]
	v_cmp_lt_i32_e64 s[0:1], 16, v159
	v_cmp_lt_i32_e64 s[8:9], 17, v159
	v_cmp_lt_i32_e64 s[10:11], 18, v159
	v_cmp_lt_i32_e64 s[12:13], 19, v159
	v_cndmask_b32_e64 v90, v231, v90, s[0:1]
	v_cndmask_b32_e64 v91, v231, v91, s[8:9]
	v_cndmask_b32_e64 v92, v231, v92, s[10:11]
	v_cndmask_b32_e64 v93, v231, v93, s[12:13]
	v_cmp_lt_i32_e64 s[0:1], 24, v159
	v_cmp_lt_i32_e64 s[8:9], 25, v159
	v_cmp_lt_i32_e64 s[10:11], 26, v159
	v_cmp_lt_i32_e64 s[12:13], 27, v159
	v_cndmask_b32_e64 v94, v231, v94, s[0:1]
	v_cndmask_b32_e64 v95, v231, v95, s[8:9]
	v_cndmask_b32_e64 v96, v231, v96, s[10:11]
	v_cndmask_b32_e64 v97, v231, v97, s[12:13]

.Lstk_nm0:
	v_exp_f32_e64 v200, -|v66|
	v_exp_f32_e64 v201, -|v67|
	v_exp_f32_e64 v202, -|v68|
	v_exp_f32_e64 v203, -|v69|
	v_pk_add_f32 v[200:201], v[200:201], v[236:237] op_sel_hi:[1,0]
	v_max_i32_e32 v174, 0, v66
	v_max_i32_e32 v175, 0, v67
	v_log_f32_e32 v200, v200
	v_log_f32_e32 v201, v201
	v_exp_f32_e64 v204, -|v70|
	v_exp_f32_e64 v205, -|v71|
	v_pk_add_f32 v[202:203], v[202:203], v[236:237] op_sel_hi:[1,0]
	v_max_i32_e32 v176, 0, v68
	v_max_i32_e32 v177, 0, v69
	v_log_f32_e32 v202, v202
	v_log_f32_e32 v203, v203
	v_pk_add_f32 v[200:201], v[200:201], v[174:175]
	v_pk_add_f32 v[66:67], v[66:67], v[200:201] neg_lo:[0,1] neg_hi:[0,1]
	v_exp_f32_e64 v206, -|v72|
	v_exp_f32_e64 v207, -|v73|
	v_pk_add_f32 v[204:205], v[204:205], v[236:237] op_sel_hi:[1,0]
	v_max_i32_e32 v174, 0, v70
	v_max_i32_e32 v175, 0, v71
	v_log_f32_e32 v204, v204
	v_log_f32_e32 v205, v205
	v_pk_add_f32 v[202:203], v[202:203], v[176:177]
	v_pk_add_f32 v[68:69], v[68:69], v[202:203] neg_lo:[0,1] neg_hi:[0,1]
	v_exp_f32_e64 v208, -|v74|
	v_exp_f32_e64 v209, -|v75|
	v_pk_add_f32 v[206:207], v[206:207], v[236:237] op_sel_hi:[1,0]
	v_max_i32_e32 v176, 0, v72
	v_max_i32_e32 v177, 0, v73
	v_log_f32_e32 v206, v206
	v_log_f32_e32 v207, v207
	v_pk_add_f32 v[204:205], v[204:205], v[174:175]
	v_pk_add_f32 v[70:71], v[70:71], v[204:205] neg_lo:[0,1] neg_hi:[0,1]
	v_exp_f32_e64 v210, -|v76|
	v_exp_f32_e64 v211, -|v77|
	v_pk_add_f32 v[208:209], v[208:209], v[236:237] op_sel_hi:[1,0]
	v_max_i32_e32 v174, 0, v74
	v_max_i32_e32 v175, 0, v75
	v_log_f32_e32 v208, v208
	v_log_f32_e32 v209, v209
	v_pk_add_f32 v[206:207], v[206:207], v[176:177]
	v_pk_add_f32 v[72:73], v[72:73], v[206:207] neg_lo:[0,1] neg_hi:[0,1]
	v_exp_f32_e64 v212, -|v78|
	v_exp_f32_e64 v213, -|v79|
	v_pk_add_f32 v[210:211], v[210:211], v[236:237] op_sel_hi:[1,0]
	v_max_i32_e32 v176, 0, v76
	v_max_i32_e32 v177, 0, v77
	v_log_f32_e32 v210, v210
	v_log_f32_e32 v211, v211
	v_pk_add_f32 v[208:209], v[208:209], v[174:175]
	v_pk_add_f32 v[74:75], v[74:75], v[208:209] neg_lo:[0,1] neg_hi:[0,1]
	v_exp_f32_e64 v214, -|v80|
	v_exp_f32_e64 v215, -|v81|
	v_pk_add_f32 v[212:213], v[212:213], v[236:237] op_sel_hi:[1,0]
	v_max_i32_e32 v174, 0, v78
	v_max_i32_e32 v175, 0, v79
	v_log_f32_e32 v212, v212
	v_log_f32_e32 v213, v213
	v_pk_add_f32 v[210:211], v[210:211], v[176:177]
	v_pk_add_f32 v[76:77], v[76:77], v[210:211] neg_lo:[0,1] neg_hi:[0,1]
	v_pk_add_f32 v[214:215], v[214:215], v[236:237] op_sel_hi:[1,0]
	v_max_i32_e32 v176, 0, v80
	v_max_i32_e32 v177, 0, v81
	v_log_f32_e32 v214, v214
	v_log_f32_e32 v215, v215
	v_pk_add_f32 v[212:213], v[212:213], v[174:175]
	v_pk_add_f32 v[78:79], v[78:79], v[212:213] neg_lo:[0,1] neg_hi:[0,1]
	v_pk_add_f32 v[214:215], v[214:215], v[176:177]
	v_pk_add_f32 v[80:81], v[80:81], v[214:215] neg_lo:[0,1] neg_hi:[0,1]
	v_pk_add_f32 v[174:175], v[200:201], v[202:203]
	v_add_f32_e32 v216, v174, v175
	v_mov_b32_e32 v220, v216
	v_pk_add_f32 v[176:177], v[204:205], v[206:207]
	v_add_f32_e32 v217, v176, v177
	v_mov_b32_e32 v221, v217
	v_pk_add_f32 v[174:175], v[208:209], v[210:211]
	v_add_f32_e32 v218, v174, v175
	v_mov_b32_e32 v222, v218
	v_pk_add_f32 v[176:177], v[212:213], v[214:215]
	v_add_f32_e32 v219, v176, v177
	v_mov_b32_e32 v223, v219
	s_nop 1
	v_permlane32_swap_b32_e32 v216, v220
	v_permlane32_swap_b32_e32 v217, v221
	v_permlane32_swap_b32_e32 v218, v222
	v_permlane32_swap_b32_e32 v219, v223
	v_add_f32_e32 v216, v216, v220
	v_cndmask_b32_e64 v220, 0, v220, s[4:5]
	v_add_f32_e32 v217, v217, v221
	v_cndmask_b32_e64 v221, 0, v221, s[4:5]
	v_add_f32_e32 v218, v218, v222
	v_cndmask_b32_e64 v222, 0, v222, s[4:5]
	v_add_f32_e32 v219, v219, v223
	v_cndmask_b32_e64 v223, 0, v223, s[4:5]
	v_add_f32_e32 v224, v219, v218
	v_add_f32_e32 v225, v224, v217
	v_add_f32_e32 v230, v225, v216
	v_sub_f32_e32 v233, v182, v223
	v_sub_f32_e32 v232, v233, v215
	v_sub_f32_e32 v229, v232, v214
	v_sub_f32_e32 v228, v229, v213
	v_pk_add_f32 v[80:81], v[80:81], v[232:233]
	v_pk_add_f32 v[78:79], v[78:79], v[228:229]
	v_exp_f32_e32 v80, v80
	v_exp_f32_e32 v81, v81
	v_exp_f32_e32 v78, v78
	v_exp_f32_e32 v79, v79
	v_sub_f32_e32 v227, v182, v219
	v_sub_f32_e32 v177, v227, v222
	v_sub_f32_e32 v176, v177, v211
	v_sub_f32_e32 v235, v176, v210
	v_sub_f32_e32 v234, v235, v209
	v_pk_add_f32 v[76:77], v[76:77], v[176:177]
	v_pk_add_f32 v[74:75], v[74:75], v[234:235]
	v_exp_f32_e32 v76, v76
	v_exp_f32_e32 v77, v77
	v_exp_f32_e32 v74, v74
	v_exp_f32_e32 v75, v75
	v_sub_f32_e32 v226, v182, v224
	v_sub_f32_e32 v233, v226, v221
	v_sub_f32_e32 v232, v233, v207
	v_sub_f32_e32 v229, v232, v206
	v_sub_f32_e32 v228, v229, v205
	v_pk_add_f32 v[72:73], v[72:73], v[232:233]
	v_pk_add_f32 v[70:71], v[70:71], v[228:229]
	v_exp_f32_e32 v72, v72
	v_exp_f32_e32 v73, v73
	v_exp_f32_e32 v70, v70
	v_exp_f32_e32 v71, v71
	v_sub_f32_e32 v227, v182, v225
	v_sub_f32_e32 v177, v227, v220
	v_sub_f32_e32 v176, v177, v203
	v_sub_f32_e32 v235, v176, v202
	v_sub_f32_e32 v234, v235, v201
	v_pk_add_f32 v[68:69], v[68:69], v[176:177]
	v_pk_add_f32 v[66:67], v[66:67], v[234:235]
	v_exp_f32_e32 v68, v68
	v_exp_f32_e32 v69, v69
	v_exp_f32_e32 v66, v66
	v_exp_f32_e32 v67, v67
	v_add_f32_e64 v173, -v183, -v230
	v_add_u32_e32 v0, v0, v191
	v_cvt_pk_bf16_f32 v66, v66, v67
	v_cvt_pk_bf16_f32 v67, v68, v69
	v_cvt_pk_bf16_f32 v68, v70, v71
	v_cvt_pk_bf16_f32 v69, v72, v73
	v_cvt_pk_bf16_f32 v70, v74, v75
	v_cvt_pk_bf16_f32 v71, v76, v77
	v_cvt_pk_bf16_f32 v72, v78, v79
	v_cvt_pk_bf16_f32 v73, v80, v81
	v_cvt_pk_bf16_f32 v74, v82, v83
	v_cvt_pk_bf16_f32 v75, v84, v85
	v_cvt_pk_bf16_f32 v76, v86, v87
	v_cvt_pk_bf16_f32 v77, v88, v89
	v_cvt_pk_bf16_f32 v78, v90, v91
	v_cvt_pk_bf16_f32 v79, v92, v93
	v_cvt_pk_bf16_f32 v80, v94, v95
	v_cvt_pk_bf16_f32 v81, v96, v97
	ds_read_b128 v[82:85], v0 offset:17408
	ds_read_b128 v[86:89], v0 offset:22016
	ds_read_b128 v[90:93], v0 offset:26624
	ds_read_b128 v[94:97], v0 offset:31232
	s_waitcnt lgkmcnt(3)
	v_mfma_f32_32x32x16_bf16 v[50:65], v[82:85], v[66:69], v[50:65]
	s_waitcnt lgkmcnt(2)
	v_mfma_f32_32x32x16_bf16 v[34:49], v[86:89], v[66:69], v[34:49]
	s_waitcnt lgkmcnt(1)
	v_mfma_f32_32x32x16_bf16 v[18:33], v[90:93], v[66:69], v[18:33]
	s_waitcnt lgkmcnt(0)
	v_mfma_f32_32x32x16_bf16 v[2:17], v[94:97], v[66:69], v[2:17]
	ds_read_b128 v[66:69], v0 offset:17440
	ds_read_b128 v[82:85], v0 offset:22048
	ds_read_b128 v[86:89], v0 offset:26656
	ds_read_b128 v[90:93], v0 offset:31264
	s_waitcnt lgkmcnt(3)
	v_mfma_f32_32x32x16_bf16 v[50:65], v[66:69], v[70:73], v[50:65]
	s_waitcnt lgkmcnt(2)
	v_mfma_f32_32x32x16_bf16 v[34:49], v[82:85], v[70:73], v[34:49]
	s_waitcnt lgkmcnt(1)
	v_mfma_f32_32x32x16_bf16 v[18:33], v[86:89], v[70:73], v[18:33]
	s_waitcnt lgkmcnt(0)
	v_mfma_f32_32x32x16_bf16 v[2:17], v[90:93], v[70:73], v[2:17]
	ds_read_b128 v[66:69], v0 offset:17472
	ds_read_b128 v[70:73], v0 offset:22080
	ds_read_b128 v[82:85], v0 offset:26688
	ds_read_b128 v[86:89], v0 offset:31296
	s_waitcnt lgkmcnt(3)
	v_mfma_f32_32x32x16_bf16 v[50:65], v[66:69], v[74:77], v[50:65]
	s_waitcnt lgkmcnt(2)
	v_mfma_f32_32x32x16_bf16 v[34:49], v[70:73], v[74:77], v[34:49]
	s_waitcnt lgkmcnt(1)
	v_mfma_f32_32x32x16_bf16 v[18:33], v[82:85], v[74:77], v[18:33]
	s_waitcnt lgkmcnt(0)
	v_mfma_f32_32x32x16_bf16 v[2:17], v[86:89], v[74:77], v[2:17]
	ds_read_b128 v[66:69], v0 offset:17504
	ds_read_b128 v[70:73], v0 offset:22112
	ds_read_b128 v[74:77], v0 offset:26720
	ds_read_b128 v[82:85], v0 offset:31328
	s_waitcnt lgkmcnt(3)
	v_mfma_f32_32x32x16_bf16 v[50:65], v[66:69], v[78:81], v[50:65]
	s_waitcnt lgkmcnt(2)
	v_mfma_f32_32x32x16_bf16 v[34:49], v[70:73], v[78:81], v[34:49]
	s_waitcnt lgkmcnt(1)
	v_mfma_f32_32x32x16_bf16 v[18:33], v[74:77], v[78:81], v[18:33]
	s_waitcnt lgkmcnt(0)
	v_mfma_f32_32x32x16_bf16 v[2:17], v[82:85], v[78:81], v[2:17]
	v_add_f32_e32 v172, v172, v173
